# GLA scan phase: sample-state loop issues its 3 independent global loads together (1 exposed latency per iteration instead of 3)
# speedup vs baseline: 1.0110x; 1.0110x over previous
.LBB0_4206:
	v_lshl_add_u64 v[12:13], v[2:3], 0, s[20:21]
	global_load_dwordx4 v[12:15], v[12:13], off
	global_load_dwordx2 v[28:29], v[6:7], off
	global_load_dwordx4 v[30:33], v[4:5], off
	s_mov_b64 s[2:3], 0xc00
	s_waitcnt vmcnt(2)
	ds_write2_b32 v10, v12, v13 offset1:1
	ds_write2_b32 v10, v14, v15 offset0:2 offset1:3
	s_waitcnt lgkmcnt(0)
	s_barrier
	ds_read_b32 v16, v8
	ds_read2_b32 v[18:19], v9 offset0:33 offset1:66
	ds_read_b32 v21, v9 offset:396
	s_waitcnt lgkmcnt(1)
	v_mov_b32_e32 v20, v19
	v_mov_b32_e32 v17, v18
	s_waitcnt vmcnt(1)
	v_lshlrev_b32_e32 v22, 16, v28
	v_and_b32_e32 v23, 0xffff0000, v28
	v_lshlrev_b32_e32 v24, 16, v29
	v_and_b32_e32 v25, 0xffff0000, v29
	v_cvt_pk_bf16_f32 v26, v16, v18
	s_waitcnt lgkmcnt(0)
	v_cvt_pk_bf16_f32 v27, v19, v21
	global_store_dwordx2 v[6:7], v[26:27], off
	s_barrier
	v_lshl_add_u64 v[4:5], v[4:5], 0, s[2:3]
	s_mov_b64 s[2:3], 0x90000
	v_lshl_add_u64 v[6:7], v[6:7], 0, s[2:3]
	s_waitcnt vmcnt(1)
	v_pk_fma_f32 v[14:15], v[20:21], v[32:33], v[24:25]
	v_pk_fma_f32 v[12:13], v[16:17], v[30:31], v[22:23]
	ds_write_b32 v8, v12
	ds_write2_b32 v9, v13, v14 offset0:33 offset1:66
	ds_write_b32 v9, v15 offset:396
	s_waitcnt lgkmcnt(0)
	s_barrier
	ds_read2_b32 v[12:13], v10 offset1:1
	ds_read2_b32 v[14:15], v10 offset0:2 offset1:3
	v_lshl_add_u64 v[16:17], v[0:1], 0, s[20:21]
	s_add_u32 s20, s20, 0x120000
	s_addc_u32 s21, s21, 0
	s_cmp_lg_u32 s20, 0x900000
	s_waitcnt lgkmcnt(0)
	global_store_dwordx4 v[16:17], v[12:15], off
	s_barrier
	s_cbranch_scc1 .LBB0_4206
